# residual GEMM epilogues (FFN1-down, w_o, FFN2-down) rewritten row-group major: each wave loads/stores the four 64B pieces of a row back to back, 16 loads in flight, counted waits
# speedup vs baseline: 1.0018x; 1.0018x over previous
.LBB0_361:
	v_lshl_add_u32 v128, s69, 8, v221
	v_lshl_or_b32 v136, s70, 8, v223
	s_ashr_i32 s2, s69, 4
	v_lshlrev_b32_e32 v136, 2, v136
	s_mul_hi_i32 s32, s2, 0x9000
	s_mul_i32 s2, s2, 0x9000
	v_lshl_add_u32 v128, v128, 12, v136
	s_add_u32 s34, s52, s2
	s_addc_u32 s35, s53, s32
	v_add_u32_e32 v129, 0x10000, v128
	v_add_u32_e32 v130, 0x20000, v128
	v_add_u32_e32 v131, 0x30000, v128
	v_add_u32_e32 v132, 0x80000, v128
	v_add_u32_e32 v133, 0x90000, v128
	v_add_u32_e32 v134, 0xa0000, v128
	v_add_u32_e32 v135, 0xb0000, v128
	global_load_dwordx4 v[140:143], v136, s[34:35]
	global_load_dwordx4 v[144:147], v136, s[34:35] offset:64
	global_load_dwordx4 v[148:151], v136, s[34:35] offset:512
	global_load_dwordx4 v[152:155], v136, s[34:35] offset:576
	global_load_dwordx4 v[188:191], v128, s[0:1]
	global_load_dwordx4 v[192:195], v128, s[0:1] offset:64
	global_load_dwordx4 v[196:199], v128, s[0:1] offset:512
	global_load_dwordx4 v[200:203], v128, s[0:1] offset:576
	global_load_dwordx4 v[204:207], v129, s[0:1]
	global_load_dwordx4 v[208:211], v129, s[0:1] offset:64
	global_load_dwordx4 v[212:215], v129, s[0:1] offset:512
	global_load_dwordx4 v[216:219], v129, s[0:1] offset:576
	global_load_dwordx4 v[156:159], v130, s[0:1]
	global_load_dwordx4 v[160:163], v130, s[0:1] offset:64
	global_load_dwordx4 v[164:167], v130, s[0:1] offset:512
	global_load_dwordx4 v[168:171], v130, s[0:1] offset:576
	global_load_dwordx4 v[236:239], v131, s[0:1]
	global_load_dwordx4 v[240:243], v131, s[0:1] offset:64
	global_load_dwordx4 v[244:247], v131, s[0:1] offset:512
	global_load_dwordx4 v[248:251], v131, s[0:1] offset:576
	s_waitcnt vmcnt(8)
	v_pk_mul_f32 v[140:141], v[140:141], 0.5 op_sel_hi:[1,0]
	v_pk_mul_f32 v[142:143], v[142:143], 0.5 op_sel_hi:[1,0]
	v_pk_mul_f32 v[144:145], v[144:145], 0.5 op_sel_hi:[1,0]
	v_pk_mul_f32 v[146:147], v[146:147], 0.5 op_sel_hi:[1,0]
	v_pk_mul_f32 v[148:149], v[148:149], 0.5 op_sel_hi:[1,0]
	v_pk_mul_f32 v[150:151], v[150:151], 0.5 op_sel_hi:[1,0]
	v_pk_mul_f32 v[152:153], v[152:153], 0.5 op_sel_hi:[1,0]
	v_pk_mul_f32 v[154:155], v[154:155], 0.5 op_sel_hi:[1,0]
	v_pk_fma_f32 v[188:189], v[124:125], v[140:141], v[188:189]
	v_pk_fma_f32 v[190:191], v[126:127], v[142:143], v[190:191]
	v_pk_fma_f32 v[192:193], v[104:105], v[144:145], v[192:193]
	v_pk_fma_f32 v[194:195], v[106:107], v[146:147], v[194:195]
	v_pk_fma_f32 v[196:197], v[68:69], v[148:149], v[196:197]
	v_pk_fma_f32 v[198:199], v[70:71], v[150:151], v[198:199]
	v_pk_fma_f32 v[200:201], v[44:45], v[152:153], v[200:201]
	v_pk_fma_f32 v[202:203], v[46:47], v[154:155], v[202:203]
	global_store_dwordx4 v128, v[188:191], s[8:9]
	global_store_dwordx4 v128, v[192:195], s[8:9] offset:64
	global_store_dwordx4 v128, v[196:199], s[8:9] offset:512
	global_store_dwordx4 v128, v[200:203], s[8:9] offset:576
	v_pk_fma_f32 v[204:205], v[120:121], v[140:141], v[204:205]
	v_pk_fma_f32 v[206:207], v[122:123], v[142:143], v[206:207]
	v_pk_fma_f32 v[208:209], v[96:97], v[144:145], v[208:209]
	v_pk_fma_f32 v[210:211], v[98:99], v[146:147], v[210:211]
	v_pk_fma_f32 v[212:213], v[64:65], v[148:149], v[212:213]
	v_pk_fma_f32 v[214:215], v[66:67], v[150:151], v[214:215]
	v_pk_fma_f32 v[216:217], v[36:37], v[152:153], v[216:217]
	v_pk_fma_f32 v[218:219], v[38:39], v[154:155], v[218:219]
	global_store_dwordx4 v129, v[204:207], s[8:9]
	global_store_dwordx4 v129, v[208:211], s[8:9] offset:64
	global_store_dwordx4 v129, v[212:215], s[8:9] offset:512
	global_store_dwordx4 v129, v[216:219], s[8:9] offset:576
	s_nop 1
	global_load_dwordx4 v[188:191], v132, s[0:1]
	global_load_dwordx4 v[192:195], v132, s[0:1] offset:64
	global_load_dwordx4 v[196:199], v132, s[0:1] offset:512
	global_load_dwordx4 v[200:203], v132, s[0:1] offset:576
	global_load_dwordx4 v[204:207], v133, s[0:1]
	global_load_dwordx4 v[208:211], v133, s[0:1] offset:64
	global_load_dwordx4 v[212:215], v133, s[0:1] offset:512
	global_load_dwordx4 v[216:219], v133, s[0:1] offset:576
	s_waitcnt vmcnt(16)
	v_pk_fma_f32 v[156:157], v[116:117], v[140:141], v[156:157]
	v_pk_fma_f32 v[158:159], v[118:119], v[142:143], v[158:159]
	v_pk_fma_f32 v[160:161], v[88:89], v[144:145], v[160:161]
	v_pk_fma_f32 v[162:163], v[90:91], v[146:147], v[162:163]
	v_pk_fma_f32 v[164:165], v[52:53], v[148:149], v[164:165]
	v_pk_fma_f32 v[166:167], v[54:55], v[150:151], v[166:167]
	v_pk_fma_f32 v[168:169], v[28:29], v[152:153], v[168:169]
	v_pk_fma_f32 v[170:171], v[30:31], v[154:155], v[170:171]
	global_store_dwordx4 v130, v[156:159], s[8:9]
	global_store_dwordx4 v130, v[160:163], s[8:9] offset:64
	global_store_dwordx4 v130, v[164:167], s[8:9] offset:512
	global_store_dwordx4 v130, v[168:171], s[8:9] offset:576
	v_pk_fma_f32 v[236:237], v[112:113], v[140:141], v[236:237]
	v_pk_fma_f32 v[238:239], v[114:115], v[142:143], v[238:239]
	v_pk_fma_f32 v[240:241], v[80:81], v[144:145], v[240:241]
	v_pk_fma_f32 v[242:243], v[82:83], v[146:147], v[242:243]
	v_pk_fma_f32 v[244:245], v[48:49], v[148:149], v[244:245]
	v_pk_fma_f32 v[246:247], v[50:51], v[150:151], v[246:247]
	v_pk_fma_f32 v[248:249], v[20:21], v[152:153], v[248:249]
	v_pk_fma_f32 v[250:251], v[22:23], v[154:155], v[250:251]
	global_store_dwordx4 v131, v[236:239], s[8:9]
	global_store_dwordx4 v131, v[240:243], s[8:9] offset:64
	global_store_dwordx4 v131, v[244:247], s[8:9] offset:512
	global_store_dwordx4 v131, v[248:251], s[8:9] offset:576
	s_nop 1
	global_load_dwordx4 v[156:159], v134, s[0:1]
	global_load_dwordx4 v[160:163], v134, s[0:1] offset:64
	global_load_dwordx4 v[164:167], v134, s[0:1] offset:512
	global_load_dwordx4 v[168:171], v134, s[0:1] offset:576
	global_load_dwordx4 v[236:239], v135, s[0:1]
	global_load_dwordx4 v[240:243], v135, s[0:1] offset:64
	global_load_dwordx4 v[244:247], v135, s[0:1] offset:512
	global_load_dwordx4 v[248:251], v135, s[0:1] offset:576
	s_waitcnt vmcnt(16)
	v_pk_fma_f32 v[188:189], v[108:109], v[140:141], v[188:189]
	v_pk_fma_f32 v[190:191], v[110:111], v[142:143], v[190:191]
	v_pk_fma_f32 v[192:193], v[76:77], v[144:145], v[192:193]
	v_pk_fma_f32 v[194:195], v[78:79], v[146:147], v[194:195]
	v_pk_fma_f32 v[196:197], v[40:41], v[148:149], v[196:197]
	v_pk_fma_f32 v[198:199], v[42:43], v[150:151], v[198:199]
	v_pk_fma_f32 v[200:201], v[12:13], v[152:153], v[200:201]
	v_pk_fma_f32 v[202:203], v[14:15], v[154:155], v[202:203]
	global_store_dwordx4 v132, v[188:191], s[8:9]
	global_store_dwordx4 v132, v[192:195], s[8:9] offset:64
	global_store_dwordx4 v132, v[196:199], s[8:9] offset:512
	global_store_dwordx4 v132, v[200:203], s[8:9] offset:576
	v_pk_fma_f32 v[204:205], v[100:101], v[140:141], v[204:205]
	v_pk_fma_f32 v[206:207], v[102:103], v[142:143], v[206:207]
	v_pk_fma_f32 v[208:209], v[72:73], v[144:145], v[208:209]
	v_pk_fma_f32 v[210:211], v[74:75], v[146:147], v[210:211]
	v_pk_fma_f32 v[212:213], v[32:33], v[148:149], v[212:213]
	v_pk_fma_f32 v[214:215], v[34:35], v[150:151], v[214:215]
	v_pk_fma_f32 v[216:217], v[8:9], v[152:153], v[216:217]
	v_pk_fma_f32 v[218:219], v[10:11], v[154:155], v[218:219]
	global_store_dwordx4 v133, v[204:207], s[8:9]
	global_store_dwordx4 v133, v[208:211], s[8:9] offset:64
	global_store_dwordx4 v133, v[212:215], s[8:9] offset:512
	global_store_dwordx4 v133, v[216:219], s[8:9] offset:576
	s_waitcnt vmcnt(8)
	v_pk_fma_f32 v[156:157], v[92:93], v[140:141], v[156:157]
	v_pk_fma_f32 v[158:159], v[94:95], v[142:143], v[158:159]
	v_pk_fma_f32 v[160:161], v[60:61], v[144:145], v[160:161]
	v_pk_fma_f32 v[162:163], v[62:63], v[146:147], v[162:163]
	v_pk_fma_f32 v[164:165], v[24:25], v[148:149], v[164:165]
	v_pk_fma_f32 v[166:167], v[26:27], v[150:151], v[166:167]
	v_pk_fma_f32 v[168:169], v[4:5], v[152:153], v[168:169]
	v_pk_fma_f32 v[170:171], v[6:7], v[154:155], v[170:171]
	global_store_dwordx4 v134, v[156:159], s[8:9]
	global_store_dwordx4 v134, v[160:163], s[8:9] offset:64
	global_store_dwordx4 v134, v[164:167], s[8:9] offset:512
	global_store_dwordx4 v134, v[168:171], s[8:9] offset:576
	v_pk_fma_f32 v[236:237], v[84:85], v[140:141], v[236:237]
	v_pk_fma_f32 v[238:239], v[86:87], v[142:143], v[238:239]
	v_pk_fma_f32 v[240:241], v[56:57], v[144:145], v[240:241]
	v_pk_fma_f32 v[242:243], v[58:59], v[146:147], v[242:243]
	v_pk_fma_f32 v[244:245], v[16:17], v[148:149], v[244:245]
	v_pk_fma_f32 v[246:247], v[18:19], v[150:151], v[246:247]
	v_pk_fma_f32 v[248:249], v[0:1], v[152:153], v[248:249]
	v_pk_fma_f32 v[250:251], v[2:3], v[154:155], v[250:251]
	global_store_dwordx4 v135, v[236:239], s[8:9]
	global_store_dwordx4 v135, v[240:243], s[8:9] offset:64
	global_store_dwordx4 v135, v[244:247], s[8:9] offset:512
	global_store_dwordx4 v135, v[248:251], s[8:9] offset:576
	s_mov_b64 s[34:35], -1
	s_and_b64 vcc, exec, s[4:5]
	s_cbranch_vccnz .LBB0_346
	s_andn2_b64 vcc, exec, s[14:15]
	s_cbranch_vccnz .LBB0_345
	s_barrier
	s_branch .LBB0_345

.LBB0_1203:
	v_lshl_add_u32 v128, s38, 8, v206
	v_lshl_or_b32 v136, s39, 8, v208
	s_ashr_i32 s2, s38, 4
	v_lshlrev_b32_e32 v136, 2, v136
	s_mul_hi_i32 s29, s2, 0x9000
	s_mul_i32 s2, s2, 0x9000
	v_lshl_add_u32 v128, v128, 12, v136
	s_add_u32 s38, s58, s2
	s_addc_u32 s39, s59, s29
	v_add_u32_e32 v129, 0x10000, v128
	v_add_u32_e32 v130, 0x20000, v128
	v_add_u32_e32 v131, 0x30000, v128
	v_add_u32_e32 v132, 0x80000, v128
	v_add_u32_e32 v133, 0x90000, v128
	v_add_u32_e32 v134, 0xa0000, v128
	v_add_u32_e32 v135, 0xb0000, v128
	global_load_dwordx4 v[140:143], v136, s[38:39]
	global_load_dwordx4 v[144:147], v136, s[38:39] offset:64
	global_load_dwordx4 v[148:151], v136, s[38:39] offset:512
	global_load_dwordx4 v[152:155], v136, s[38:39] offset:576
	global_load_dwordx4 v[180:183], v128, s[8:9]
	global_load_dwordx4 v[184:187], v128, s[8:9] offset:64
	global_load_dwordx4 v[188:191], v128, s[8:9] offset:512
	global_load_dwordx4 v[192:195], v128, s[8:9] offset:576
	global_load_dwordx4 v[196:199], v129, s[8:9]
	global_load_dwordx4 v[200:203], v129, s[8:9] offset:64
	global_load_dwordx4 v[212:215], v129, s[8:9] offset:512
	global_load_dwordx4 v[216:219], v129, s[8:9] offset:576
	global_load_dwordx4 v[220:223], v130, s[8:9]
	global_load_dwordx4 v[224:227], v130, s[8:9] offset:64
	global_load_dwordx4 v[232:235], v130, s[8:9] offset:512
	global_load_dwordx4 v[236:239], v130, s[8:9] offset:576
	global_load_dwordx4 v[240:243], v131, s[8:9]
	global_load_dwordx4 v[244:247], v131, s[8:9] offset:64
	global_load_dwordx4 v[248:251], v131, s[8:9] offset:512
	global_load_dwordx4 v[156:159], v131, s[8:9] offset:576
	s_waitcnt vmcnt(8)
	v_pk_fma_f32 v[180:181], v[124:125], v[140:141], v[180:181]
	v_pk_fma_f32 v[182:183], v[126:127], v[142:143], v[182:183]
	v_pk_fma_f32 v[184:185], v[100:101], v[144:145], v[184:185]
	v_pk_fma_f32 v[186:187], v[102:103], v[146:147], v[186:187]
	v_pk_fma_f32 v[188:189], v[68:69], v[148:149], v[188:189]
	v_pk_fma_f32 v[190:191], v[70:71], v[150:151], v[190:191]
	v_pk_fma_f32 v[192:193], v[44:45], v[152:153], v[192:193]
	v_pk_fma_f32 v[194:195], v[46:47], v[154:155], v[194:195]
	global_store_dwordx4 v128, v[180:183], s[8:9]
	global_store_dwordx4 v128, v[184:187], s[8:9] offset:64
	global_store_dwordx4 v128, v[188:191], s[8:9] offset:512
	global_store_dwordx4 v128, v[192:195], s[8:9] offset:576
	v_pk_fma_f32 v[196:197], v[120:121], v[140:141], v[196:197]
	v_pk_fma_f32 v[198:199], v[122:123], v[142:143], v[198:199]
	v_pk_fma_f32 v[200:201], v[96:97], v[144:145], v[200:201]
	v_pk_fma_f32 v[202:203], v[98:99], v[146:147], v[202:203]
	v_pk_fma_f32 v[212:213], v[64:65], v[148:149], v[212:213]
	v_pk_fma_f32 v[214:215], v[66:67], v[150:151], v[214:215]
	v_pk_fma_f32 v[216:217], v[36:37], v[152:153], v[216:217]
	v_pk_fma_f32 v[218:219], v[38:39], v[154:155], v[218:219]
	global_store_dwordx4 v129, v[196:199], s[8:9]
	global_store_dwordx4 v129, v[200:203], s[8:9] offset:64
	global_store_dwordx4 v129, v[212:215], s[8:9] offset:512
	global_store_dwordx4 v129, v[216:219], s[8:9] offset:576
	s_nop 1
	global_load_dwordx4 v[180:183], v132, s[8:9]
	global_load_dwordx4 v[184:187], v132, s[8:9] offset:64
	global_load_dwordx4 v[188:191], v132, s[8:9] offset:512
	global_load_dwordx4 v[192:195], v132, s[8:9] offset:576
	global_load_dwordx4 v[196:199], v133, s[8:9]
	global_load_dwordx4 v[200:203], v133, s[8:9] offset:64
	global_load_dwordx4 v[212:215], v133, s[8:9] offset:512
	global_load_dwordx4 v[216:219], v133, s[8:9] offset:576
	s_waitcnt vmcnt(16)
	v_pk_fma_f32 v[220:221], v[116:117], v[140:141], v[220:221]
	v_pk_fma_f32 v[222:223], v[118:119], v[142:143], v[222:223]
	v_pk_fma_f32 v[224:225], v[88:89], v[144:145], v[224:225]
	v_pk_fma_f32 v[226:227], v[90:91], v[146:147], v[226:227]
	v_pk_fma_f32 v[232:233], v[52:53], v[148:149], v[232:233]
	v_pk_fma_f32 v[234:235], v[54:55], v[150:151], v[234:235]
	v_pk_fma_f32 v[236:237], v[28:29], v[152:153], v[236:237]
	v_pk_fma_f32 v[238:239], v[30:31], v[154:155], v[238:239]
	global_store_dwordx4 v130, v[220:223], s[8:9]
	global_store_dwordx4 v130, v[224:227], s[8:9] offset:64
	global_store_dwordx4 v130, v[232:235], s[8:9] offset:512
	global_store_dwordx4 v130, v[236:239], s[8:9] offset:576
	v_pk_fma_f32 v[240:241], v[112:113], v[140:141], v[240:241]
	v_pk_fma_f32 v[242:243], v[114:115], v[142:143], v[242:243]
	v_pk_fma_f32 v[244:245], v[80:81], v[144:145], v[244:245]
	v_pk_fma_f32 v[246:247], v[82:83], v[146:147], v[246:247]
	v_pk_fma_f32 v[248:249], v[48:49], v[148:149], v[248:249]
	v_pk_fma_f32 v[250:251], v[50:51], v[150:151], v[250:251]
	v_pk_fma_f32 v[156:157], v[20:21], v[152:153], v[156:157]
	v_pk_fma_f32 v[158:159], v[22:23], v[154:155], v[158:159]
	global_store_dwordx4 v131, v[240:243], s[8:9]
	global_store_dwordx4 v131, v[244:247], s[8:9] offset:64
	global_store_dwordx4 v131, v[248:251], s[8:9] offset:512
	global_store_dwordx4 v131, v[156:159], s[8:9] offset:576
	s_nop 1
	global_load_dwordx4 v[220:223], v134, s[8:9]
	global_load_dwordx4 v[224:227], v134, s[8:9] offset:64
	global_load_dwordx4 v[232:235], v134, s[8:9] offset:512
	global_load_dwordx4 v[236:239], v134, s[8:9] offset:576
	global_load_dwordx4 v[240:243], v135, s[8:9]
	global_load_dwordx4 v[244:247], v135, s[8:9] offset:64
	global_load_dwordx4 v[248:251], v135, s[8:9] offset:512
	global_load_dwordx4 v[156:159], v135, s[8:9] offset:576
	s_waitcnt vmcnt(16)
	v_pk_fma_f32 v[180:181], v[108:109], v[140:141], v[180:181]
	v_pk_fma_f32 v[182:183], v[110:111], v[142:143], v[182:183]
	v_pk_fma_f32 v[184:185], v[76:77], v[144:145], v[184:185]
	v_pk_fma_f32 v[186:187], v[78:79], v[146:147], v[186:187]
	v_pk_fma_f32 v[188:189], v[40:41], v[148:149], v[188:189]
	v_pk_fma_f32 v[190:191], v[42:43], v[150:151], v[190:191]
	v_pk_fma_f32 v[192:193], v[12:13], v[152:153], v[192:193]
	v_pk_fma_f32 v[194:195], v[14:15], v[154:155], v[194:195]
	global_store_dwordx4 v132, v[180:183], s[8:9]
	global_store_dwordx4 v132, v[184:187], s[8:9] offset:64
	global_store_dwordx4 v132, v[188:191], s[8:9] offset:512
	global_store_dwordx4 v132, v[192:195], s[8:9] offset:576
	v_pk_fma_f32 v[196:197], v[104:105], v[140:141], v[196:197]
	v_pk_fma_f32 v[198:199], v[106:107], v[142:143], v[198:199]
	v_pk_fma_f32 v[200:201], v[72:73], v[144:145], v[200:201]
	v_pk_fma_f32 v[202:203], v[74:75], v[146:147], v[202:203]
	v_pk_fma_f32 v[212:213], v[32:33], v[148:149], v[212:213]
	v_pk_fma_f32 v[214:215], v[34:35], v[150:151], v[214:215]
	v_pk_fma_f32 v[216:217], v[8:9], v[152:153], v[216:217]
	v_pk_fma_f32 v[218:219], v[10:11], v[154:155], v[218:219]
	global_store_dwordx4 v133, v[196:199], s[8:9]
	global_store_dwordx4 v133, v[200:203], s[8:9] offset:64
	global_store_dwordx4 v133, v[212:215], s[8:9] offset:512
	global_store_dwordx4 v133, v[216:219], s[8:9] offset:576
	s_waitcnt vmcnt(8)
	v_pk_fma_f32 v[220:221], v[92:93], v[140:141], v[220:221]
	v_pk_fma_f32 v[222:223], v[94:95], v[142:143], v[222:223]
	v_pk_fma_f32 v[224:225], v[60:61], v[144:145], v[224:225]
	v_pk_fma_f32 v[226:227], v[62:63], v[146:147], v[226:227]
	v_pk_fma_f32 v[232:233], v[24:25], v[148:149], v[232:233]
	v_pk_fma_f32 v[234:235], v[26:27], v[150:151], v[234:235]
	v_pk_fma_f32 v[236:237], v[4:5], v[152:153], v[236:237]
	v_pk_fma_f32 v[238:239], v[6:7], v[154:155], v[238:239]
	global_store_dwordx4 v134, v[220:223], s[8:9]
	global_store_dwordx4 v134, v[224:227], s[8:9] offset:64
	global_store_dwordx4 v134, v[232:235], s[8:9] offset:512
	global_store_dwordx4 v134, v[236:239], s[8:9] offset:576
	v_pk_fma_f32 v[240:241], v[84:85], v[140:141], v[240:241]
	v_pk_fma_f32 v[242:243], v[86:87], v[142:143], v[242:243]
	v_pk_fma_f32 v[244:245], v[56:57], v[144:145], v[244:245]
	v_pk_fma_f32 v[246:247], v[58:59], v[146:147], v[246:247]
	v_pk_fma_f32 v[248:249], v[16:17], v[148:149], v[248:249]
	v_pk_fma_f32 v[250:251], v[18:19], v[150:151], v[250:251]
	v_pk_fma_f32 v[156:157], v[0:1], v[152:153], v[156:157]
	v_pk_fma_f32 v[158:159], v[2:3], v[154:155], v[158:159]
	global_store_dwordx4 v135, v[240:243], s[8:9]
	global_store_dwordx4 v135, v[244:247], s[8:9] offset:64
	global_store_dwordx4 v135, v[248:251], s[8:9] offset:512
	global_store_dwordx4 v135, v[156:159], s[8:9] offset:576
	s_mov_b64 s[38:39], -1
	s_andn2_b64 vcc, exec, s[6:7]
	s_cbranch_vccnz .LBB0_1192
	s_andn2_b64 vcc, exec, s[0:1]
	s_cbranch_vccnz .LBB0_1191
	s_barrier
	s_branch .LBB0_1191

.LBB0_1414:
	v_lshl_add_u32 v128, s66, 8, v218
	v_lshl_or_b32 v136, s67, 8, v220
	s_ashr_i32 s2, s66, 4
	v_lshlrev_b32_e32 v136, 2, v136
	s_mul_hi_i32 s31, s2, 0x9000
	s_mul_i32 s2, s2, 0x9000
	v_lshl_add_u32 v128, v128, 12, v136
	s_add_u32 s30, s50, s2
	s_addc_u32 s31, s51, s31
	v_add_u32_e32 v129, 0x10000, v128
	v_add_u32_e32 v130, 0x20000, v128
	v_add_u32_e32 v131, 0x30000, v128
	v_add_u32_e32 v132, 0x80000, v128
	v_add_u32_e32 v133, 0x90000, v128
	v_add_u32_e32 v134, 0xa0000, v128
	v_add_u32_e32 v135, 0xb0000, v128
	global_load_dwordx4 v[140:143], v136, s[30:31]
	global_load_dwordx4 v[144:147], v136, s[30:31] offset:64
	global_load_dwordx4 v[148:151], v136, s[30:31] offset:512
	global_load_dwordx4 v[152:155], v136, s[30:31] offset:576
	global_load_dwordx4 v[184:187], v128, s[8:9]
	global_load_dwordx4 v[188:191], v128, s[8:9] offset:64
	global_load_dwordx4 v[192:195], v128, s[8:9] offset:512
	global_load_dwordx4 v[196:199], v128, s[8:9] offset:576
	global_load_dwordx4 v[200:203], v129, s[8:9]
	global_load_dwordx4 v[204:207], v129, s[8:9] offset:64
	global_load_dwordx4 v[208:211], v129, s[8:9] offset:512
	global_load_dwordx4 v[212:215], v129, s[8:9] offset:576
	global_load_dwordx4 v[156:159], v130, s[8:9]
	global_load_dwordx4 v[160:163], v130, s[8:9] offset:64
	global_load_dwordx4 v[164:167], v130, s[8:9] offset:512
	global_load_dwordx4 v[168:171], v130, s[8:9] offset:576
	global_load_dwordx4 v[232:235], v131, s[8:9]
	global_load_dwordx4 v[236:239], v131, s[8:9] offset:64
	global_load_dwordx4 v[240:243], v131, s[8:9] offset:512
	global_load_dwordx4 v[244:247], v131, s[8:9] offset:576
	s_waitcnt vmcnt(8)
	v_pk_mul_f32 v[140:141], v[140:141], 0.5 op_sel_hi:[1,0]
	v_pk_mul_f32 v[142:143], v[142:143], 0.5 op_sel_hi:[1,0]
	v_pk_mul_f32 v[144:145], v[144:145], 0.5 op_sel_hi:[1,0]
	v_pk_mul_f32 v[146:147], v[146:147], 0.5 op_sel_hi:[1,0]
	v_pk_mul_f32 v[148:149], v[148:149], 0.5 op_sel_hi:[1,0]
	v_pk_mul_f32 v[150:151], v[150:151], 0.5 op_sel_hi:[1,0]
	v_pk_mul_f32 v[152:153], v[152:153], 0.5 op_sel_hi:[1,0]
	v_pk_mul_f32 v[154:155], v[154:155], 0.5 op_sel_hi:[1,0]
	v_pk_fma_f32 v[184:185], v[124:125], v[140:141], v[184:185]
	v_pk_fma_f32 v[186:187], v[126:127], v[142:143], v[186:187]
	v_pk_fma_f32 v[188:189], v[96:97], v[144:145], v[188:189]
	v_pk_fma_f32 v[190:191], v[98:99], v[146:147], v[190:191]
	v_pk_fma_f32 v[192:193], v[64:65], v[148:149], v[192:193]
	v_pk_fma_f32 v[194:195], v[66:67], v[150:151], v[194:195]
	v_pk_fma_f32 v[196:197], v[44:45], v[152:153], v[196:197]
	v_pk_fma_f32 v[198:199], v[46:47], v[154:155], v[198:199]
	global_store_dwordx4 v128, v[184:187], s[8:9]
	global_store_dwordx4 v128, v[188:191], s[8:9] offset:64
	global_store_dwordx4 v128, v[192:195], s[8:9] offset:512
	global_store_dwordx4 v128, v[196:199], s[8:9] offset:576
	v_pk_fma_f32 v[200:201], v[120:121], v[140:141], v[200:201]
	v_pk_fma_f32 v[202:203], v[122:123], v[142:143], v[202:203]
	v_pk_fma_f32 v[204:205], v[88:89], v[144:145], v[204:205]
	v_pk_fma_f32 v[206:207], v[90:91], v[146:147], v[206:207]
	v_pk_fma_f32 v[208:209], v[56:57], v[148:149], v[208:209]
	v_pk_fma_f32 v[210:211], v[58:59], v[150:151], v[210:211]
	v_pk_fma_f32 v[212:213], v[36:37], v[152:153], v[212:213]
	v_pk_fma_f32 v[214:215], v[38:39], v[154:155], v[214:215]
	global_store_dwordx4 v129, v[200:203], s[8:9]
	global_store_dwordx4 v129, v[204:207], s[8:9] offset:64
	global_store_dwordx4 v129, v[208:211], s[8:9] offset:512
	global_store_dwordx4 v129, v[212:215], s[8:9] offset:576
	s_nop 1
	global_load_dwordx4 v[184:187], v132, s[8:9]
	global_load_dwordx4 v[188:191], v132, s[8:9] offset:64
	global_load_dwordx4 v[192:195], v132, s[8:9] offset:512
	global_load_dwordx4 v[196:199], v132, s[8:9] offset:576
	global_load_dwordx4 v[200:203], v133, s[8:9]
	global_load_dwordx4 v[204:207], v133, s[8:9] offset:64
	global_load_dwordx4 v[208:211], v133, s[8:9] offset:512
	global_load_dwordx4 v[212:215], v133, s[8:9] offset:576
	s_waitcnt vmcnt(16)
	v_pk_fma_f32 v[156:157], v[116:117], v[140:141], v[156:157]
	v_pk_fma_f32 v[158:159], v[118:119], v[142:143], v[158:159]
	v_pk_fma_f32 v[160:161], v[84:85], v[144:145], v[160:161]
	v_pk_fma_f32 v[162:163], v[86:87], v[146:147], v[162:163]
	v_pk_fma_f32 v[164:165], v[52:53], v[148:149], v[164:165]
	v_pk_fma_f32 v[166:167], v[54:55], v[150:151], v[166:167]
	v_pk_fma_f32 v[168:169], v[28:29], v[152:153], v[168:169]
	v_pk_fma_f32 v[170:171], v[30:31], v[154:155], v[170:171]
	global_store_dwordx4 v130, v[156:159], s[8:9]
	global_store_dwordx4 v130, v[160:163], s[8:9] offset:64
	global_store_dwordx4 v130, v[164:167], s[8:9] offset:512
	global_store_dwordx4 v130, v[168:171], s[8:9] offset:576
	v_pk_fma_f32 v[232:233], v[112:113], v[140:141], v[232:233]
	v_pk_fma_f32 v[234:235], v[114:115], v[142:143], v[234:235]
	v_pk_fma_f32 v[236:237], v[80:81], v[144:145], v[236:237]
	v_pk_fma_f32 v[238:239], v[82:83], v[146:147], v[238:239]
	v_pk_fma_f32 v[240:241], v[48:49], v[148:149], v[240:241]
	v_pk_fma_f32 v[242:243], v[50:51], v[150:151], v[242:243]
	v_pk_fma_f32 v[244:245], v[20:21], v[152:153], v[244:245]
	v_pk_fma_f32 v[246:247], v[22:23], v[154:155], v[246:247]
	global_store_dwordx4 v131, v[232:235], s[8:9]
	global_store_dwordx4 v131, v[236:239], s[8:9] offset:64
	global_store_dwordx4 v131, v[240:243], s[8:9] offset:512
	global_store_dwordx4 v131, v[244:247], s[8:9] offset:576
	s_nop 1
	global_load_dwordx4 v[156:159], v134, s[8:9]
	global_load_dwordx4 v[160:163], v134, s[8:9] offset:64
	global_load_dwordx4 v[164:167], v134, s[8:9] offset:512
	global_load_dwordx4 v[168:171], v134, s[8:9] offset:576
	global_load_dwordx4 v[232:235], v135, s[8:9]
	global_load_dwordx4 v[236:239], v135, s[8:9] offset:64
	global_load_dwordx4 v[240:243], v135, s[8:9] offset:512
	global_load_dwordx4 v[244:247], v135, s[8:9] offset:576
	s_waitcnt vmcnt(16)
	v_pk_fma_f32 v[184:185], v[108:109], v[140:141], v[184:185]
	v_pk_fma_f32 v[186:187], v[110:111], v[142:143], v[186:187]
	v_pk_fma_f32 v[188:189], v[76:77], v[144:145], v[188:189]
	v_pk_fma_f32 v[190:191], v[78:79], v[146:147], v[190:191]
	v_pk_fma_f32 v[192:193], v[40:41], v[148:149], v[192:193]
	v_pk_fma_f32 v[194:195], v[42:43], v[150:151], v[194:195]
	v_pk_fma_f32 v[196:197], v[12:13], v[152:153], v[196:197]
	v_pk_fma_f32 v[198:199], v[14:15], v[154:155], v[198:199]
	global_store_dwordx4 v132, v[184:187], s[8:9]
	global_store_dwordx4 v132, v[188:191], s[8:9] offset:64
	global_store_dwordx4 v132, v[192:195], s[8:9] offset:512
	global_store_dwordx4 v132, v[196:199], s[8:9] offset:576
	v_pk_fma_f32 v[200:201], v[104:105], v[140:141], v[200:201]
	v_pk_fma_f32 v[202:203], v[106:107], v[142:143], v[202:203]
	v_pk_fma_f32 v[204:205], v[72:73], v[144:145], v[204:205]
	v_pk_fma_f32 v[206:207], v[74:75], v[146:147], v[206:207]
	v_pk_fma_f32 v[208:209], v[32:33], v[148:149], v[208:209]
	v_pk_fma_f32 v[210:211], v[34:35], v[150:151], v[210:211]
	v_pk_fma_f32 v[212:213], v[8:9], v[152:153], v[212:213]
	v_pk_fma_f32 v[214:215], v[10:11], v[154:155], v[214:215]
	global_store_dwordx4 v133, v[200:203], s[8:9]
	global_store_dwordx4 v133, v[204:207], s[8:9] offset:64
	global_store_dwordx4 v133, v[208:211], s[8:9] offset:512
	global_store_dwordx4 v133, v[212:215], s[8:9] offset:576
	s_waitcnt vmcnt(8)
	v_pk_fma_f32 v[156:157], v[100:101], v[140:141], v[156:157]
	v_pk_fma_f32 v[158:159], v[102:103], v[142:143], v[158:159]
	v_pk_fma_f32 v[160:161], v[68:69], v[144:145], v[160:161]
	v_pk_fma_f32 v[162:163], v[70:71], v[146:147], v[162:163]
	v_pk_fma_f32 v[164:165], v[24:25], v[148:149], v[164:165]
	v_pk_fma_f32 v[166:167], v[26:27], v[150:151], v[166:167]
	v_pk_fma_f32 v[168:169], v[4:5], v[152:153], v[168:169]
	v_pk_fma_f32 v[170:171], v[6:7], v[154:155], v[170:171]
	global_store_dwordx4 v134, v[156:159], s[8:9]
	global_store_dwordx4 v134, v[160:163], s[8:9] offset:64
	global_store_dwordx4 v134, v[164:167], s[8:9] offset:512
	global_store_dwordx4 v134, v[168:171], s[8:9] offset:576
	v_pk_fma_f32 v[232:233], v[92:93], v[140:141], v[232:233]
	v_pk_fma_f32 v[234:235], v[94:95], v[142:143], v[234:235]
	v_pk_fma_f32 v[236:237], v[60:61], v[144:145], v[236:237]
	v_pk_fma_f32 v[238:239], v[62:63], v[146:147], v[238:239]
	v_pk_fma_f32 v[240:241], v[16:17], v[148:149], v[240:241]
	v_pk_fma_f32 v[242:243], v[18:19], v[150:151], v[242:243]
	v_pk_fma_f32 v[244:245], v[0:1], v[152:153], v[244:245]
	v_pk_fma_f32 v[246:247], v[2:3], v[154:155], v[246:247]
	global_store_dwordx4 v135, v[232:235], s[8:9]
	global_store_dwordx4 v135, v[236:239], s[8:9] offset:64
	global_store_dwordx4 v135, v[240:243], s[8:9] offset:512
	global_store_dwordx4 v135, v[244:247], s[8:9] offset:576
	s_mov_b64 s[30:31], -1
	s_and_b64 vcc, exec, s[4:5]
	s_cbranch_vccnz .LBB0_1399
	s_andn2_b64 vcc, exec, s[12:13]
	s_cbranch_vccnz .LBB0_1398
	s_barrier
	s_branch .LBB0_1398
